# trimmed S5 steady-state loop + GLU epilogue with residual quads loaded up front + incremental GEMM tile scheduler, on top of the cache-policy version (re-measure)
# speedup vs baseline: 1.0443x; 1.0021x over previous
;     DI bool next(int i, Unit& u) const {
;         const long L = (long)i * G + c; if (L >= nwg) return false;
;         int wgid = (int)L; { const int q = nwg / NXCD, r = nwg % NXCD, xcd = wgid % NXCD, off = wgid / NXCD; wgid = (xcd < r ? xcd * (q + 1) : r * (q + 1) + (xcd - r) * q) + off; }
;         const int nig = WGM * nN, gid = wgid / nig, fm = gid * WGM, gsz = (nM - fm) < WGM ? (nM - fm) : WGM;
;         u.pm = fm + ((wgid % nig) % gsz); const int pv_ = (wgid % nig) / gsz; u.ks = pv_ / nNr; u.pn = pv_ - u.ks * nNr; return true;
;     }
.LBB0_654:
	s_add_i32 s25, s25, 1
	s_cmp_lt_u32 s25, 2
	s_cbranch_scc1 .Lts1_slow
	s_or_b32 s12, s89, s33
	s_and_b32 s12, s12, 7
	s_cmp_lg_u32 s12, 0
	s_cbranch_scc1 .Lts1_slow
	s_cmp_lt_u32 s52, 16
	s_cbranch_scc1 .Lts1_slow
	s_lshl_b32 s12, s90, 5
	s_cmp_gt_u32 s52, s12
	s_cbranch_scc1 .Lts1_slow
	s_mul_i32 s12, s25, s33
	s_add_i32 s12, s12, s88
	s_cmp_lt_i32 s12, s54
	s_cselect_b64 s[4:5], -1, 0
	s_cbranch_scc0 .LBB0_660
	s_lshr_b32 s12, s33, 3
	s_add_i32 s99, s99, s12
	s_cmp_ge_u32 s99, s52
	s_cselect_b32 s12, s52, 0
	s_cselect_b32 s13, 1, 0
	s_sub_i32 s99, s99, s12
	s_add_i32 s98, s98, s13
	s_cmp_ge_u32 s99, s52
	s_cselect_b32 s12, s52, 0
	s_cselect_b32 s13, 1, 0
	s_sub_i32 s99, s99, s12
	s_add_i32 s98, s98, s13
	s_lshl_b32 s77, s98, 3
	s_and_b32 s12, s99, 7
	s_add_i32 s77, s77, s12
	s_lshr_b32 s84, s99, 3
	s_mov_b32 s23, 0
	s_cmp_ge_u32 s84, s90
	s_cselect_b32 s12, s90, 0
	s_cselect_b32 s13, 1, 0
	s_sub_i32 s84, s84, s12
	s_add_i32 s23, s23, s13
	s_cmp_ge_u32 s84, s90
	s_cselect_b32 s12, s90, 0
	s_cselect_b32 s13, 1, 0
	s_sub_i32 s84, s84, s12
	s_add_i32 s23, s23, s13
	s_cmp_ge_u32 s84, s90
	s_cselect_b32 s12, s90, 0
	s_cselect_b32 s13, 1, 0
	s_sub_i32 s84, s84, s12
	s_add_i32 s23, s23, s13
	s_branch .LBB0_660
.Lts1_slow:
	s_mul_i32 s4, s25, s81
	s_mul_hi_u32 s5, s25, s33
	s_add_i32 s5, s5, s4
	s_mul_i32 s4, s25, s33
	s_add_u32 s38, s4, s88
	s_addc_u32 s39, s5, s97
	v_mov_b64_e32 v[0:1], s[54:55]
	v_cmp_ge_i64_e32 vcc, s[38:39], v[0:1]
	v_cmp_lt_i64_e64 s[4:5], s[38:39], v[0:1]
	s_cbranch_vccnz .LBB0_660
	s_ashr_i32 s12, s38, 31
	s_lshr_b32 s12, s12, 29
	s_add_i32 s23, s38, s12
	s_and_b32 s12, s23, -8
	s_sub_i32 s34, s38, s12
	s_cmp_ge_i32 s34, s96
	s_mov_b64 s[38:39], -1
	s_cbranch_scc0 .LBB0_657
	s_sub_i32 s12, s34, s96
	s_mul_i32 s12, s12, s87
	v_readlane_b32 s13, v253, 9
	s_add_i32 s35, s12, s13
	s_mov_b64 s[38:39], 0

;     DI bool next(int i, Unit& u) const {
;     ...
;         int wgid = (int)L; { const int q = nwg / NXCD, r = nwg % NXCD, xcd = wgid % NXCD, off = wgid / NXCD; wgid = (xcd < r ? xcd * (q + 1) : r * (q + 1) + (xcd - r) * q) + off; }
;         const int nig = WGM * nN, gid = wgid / nig, fm = gid * WGM, gsz = (nM - fm) < WGM ? (nM - fm) : WGM;
;         u.pm = fm + ((wgid % nig) % gsz); const int pv_ = (wgid % nig) / gsz; u.ks = pv_ / nNr; u.pn = pv_ - u.ks * nNr; return true;
.LBB0_659:
	s_ashr_i32 s12, s23, 3
	s_add_i32 s12, s35, s12
	s_abs_i32 s23, s12
	s_mul_hi_u32 s34, s23, s53
	s_mul_i32 s35, s34, s52
	s_ashr_i32 s13, s12, 31
	s_sub_i32 s23, s23, s35
	s_xor_b32 s13, s13, s51
	s_add_i32 s35, s34, 1
	s_sub_i32 s36, s23, s52
	s_cmp_ge_u32 s23, s52
	s_cselect_b32 s34, s35, s34
	s_cselect_b32 s23, s36, s23
	s_add_i32 s35, s34, 1
	s_cmp_ge_u32 s23, s52
	s_cselect_b32 s23, s35, s34
	s_xor_b32 s23, s23, s13
	s_sub_i32 s13, s23, s13
	s_lshl_b32 s23, s13, 3
	s_sub_i32 s34, s89, s23
	s_min_i32 s34, s34, 8
	s_abs_i32 s35, s34
	v_cvt_f32_u32_e32 v0, s35
	s_sub_i32 s37, 0, s35
	s_mul_i32 s13, s13, s50
	s_sub_i32 s12, s12, s13
	v_rcp_iflag_f32_e32 v0, v0
	s_abs_i32 s36, s12
	s_xor_b32 s13, s12, s34
	s_ashr_i32 s13, s13, 31
	v_mul_f32_e32 v0, 0x4f7ffffe, v0
	v_cvt_u32_f32_e32 v0, v0
	s_nop 0
	v_readfirstlane_b32 s38, v0
	s_mul_i32 s37, s37, s38
	s_mul_hi_u32 s37, s38, s37
	s_add_i32 s38, s38, s37
	s_mul_hi_u32 s37, s36, s38
	s_mul_i32 s38, s37, s35
	s_sub_i32 s36, s36, s38
	s_add_i32 s38, s37, 1
	s_sub_i32 s39, s36, s35
	s_cmp_ge_u32 s36, s35
	s_cselect_b32 s37, s38, s37
	s_cselect_b32 s36, s39, s36
	s_add_i32 s38, s37, 1
	s_cmp_ge_u32 s36, s35
	s_cselect_b32 s35, s38, s37
	s_xor_b32 s35, s35, s13
	s_sub_i32 s13, s35, s13
	s_mul_i32 s34, s13, s34
	s_sub_i32 s12, s12, s34
	s_add_i32 s77, s12, s23
	s_abs_i32 s23, s13
	s_mul_hi_u32 s34, s23, s16
	s_mul_i32 s35, s34, s90
	s_sub_i32 s23, s23, s35
	s_ashr_i32 s12, s13, 31
	s_add_i32 s35, s34, 1
	s_sub_i32 s36, s23, s90
	s_cmp_ge_u32 s23, s90
	s_cselect_b32 s34, s35, s34
	s_cselect_b32 s23, s36, s23
	s_add_i32 s35, s34, 1
	s_cmp_ge_u32 s23, s90
	s_cselect_b32 s23, s35, s34
	s_xor_b32 s23, s23, s12
	s_sub_i32 s23, s23, s12
	s_mul_i32 s12, s23, s90
	s_sub_i32 s84, s13, s12
	s_lshr_b32 s98, s77, 3
	s_mul_i32 s99, s23, s90
	s_add_i32 s99, s99, s84
	s_lshl_b32 s99, s99, 3
	s_and_b32 s12, s77, 7
	s_add_i32 s99, s99, s12

;     DI void operator()(const f32x4 (&acc)[2][2][4][2], const Unit& u, int wr, int wc, int fr, int fq) const {
;     ...
;         for (int bj = 0; bj < 2; ++bj) {
;             const int col = (col0 + bj * HALF) >> 1;
;             const f32x4 g0 = *(const f32x4*)(gp + col);
; #pragma unroll
;             for (int ai = 0; ai < 2; ++ai)
; #pragma unroll
;                 for (int m = 0; m < 4; ++m) { const size_t off = (size_t)(rbase + ai * HALF + m * 16) * D + col;
;                     const f32x4 x0 = *(const f32x4*)(src + off); const f32x4 za = acc[ai][bj][m][0], zb = acc[ai][bj][m][1]; f32x4 o;
; #pragma unroll
;                     for (int q = 0; q < 4; ++q) o[q] = za[q] / (1.f + __expf(-zb[q]));
;                     *(f32x4*)(dst + off) = x0 + g0 * o; }
.LBB0_669:
	s_lshl_b32 s12, s30, 8
	s_add_i32 s13, s12, 0xffff0000
	s_cmpk_lt_i32 s30, 0x100
	s_cselect_b32 s12, s12, s13
	s_cselect_b32 s69, s11, s15
	s_cselect_b32 s68, s10, s14
	s_cselect_b32 s67, s19, s3
	s_cselect_b32 s66, s18, s2
	v_add_u32_e32 v158, s12, v160
	s_min_i32 s12, s30, 0x100
	v_lshl_or_b32 v84, s31, 8, v162
	s_ashr_i32 s12, s12, 4
	v_ashrrev_i32_e32 v156, 1, v84
	v_ashrrev_i32_e32 v159, 31, v158
	s_mul_hi_i32 s13, s12, 0x6000
	s_mulk_i32 s12, 0x6000
	v_ashrrev_i32_e32 v157, 31, v156
	v_lshlrev_b64 v[152:153], 10, v[158:159]
	s_add_u32 s26, s79, s12
	v_lshl_add_u64 v[152:153], v[152:153], 0, v[156:157]
	s_addc_u32 s27, s80, s13
	v_lshlrev_b64 v[154:155], 2, v[152:153]
	v_lshl_add_u64 v[142:143], v[156:157], 2, s[26:27]
	v_lshl_add_u64 v[152:153], s[68:69], 0, v[154:155]
	s_mov_b64 s[12:13], 0x10000
	global_load_dwordx4 v[216:219], v[142:143], off
	global_load_dwordx4 v[220:223], v[142:143], off offset:256
	v_lshl_add_u64 v[234:235], s[66:67], 0, v[154:155]
	global_load_dwordx4 v[176:179], v[152:153], off
	global_load_dwordx4 v[180:183], v[152:153], off offset:256
	v_lshl_add_u64 v[152:153], v[152:153], 0, s[12:13]
	global_load_dwordx4 v[184:187], v[152:153], off
	global_load_dwordx4 v[188:191], v[152:153], off offset:256
	v_lshl_add_u64 v[152:153], v[152:153], 0, s[12:13]
	global_load_dwordx4 v[192:195], v[152:153], off
	global_load_dwordx4 v[196:199], v[152:153], off offset:256
	v_lshl_add_u64 v[152:153], v[152:153], 0, s[12:13]
	global_load_dwordx4 v[200:203], v[152:153], off
	global_load_dwordx4 v[204:207], v[152:153], off offset:256
	v_lshl_add_u64 v[152:153], v[152:153], 0, s[12:13]
	v_lshl_add_u64 v[152:153], v[152:153], 0, s[12:13]
	v_lshl_add_u64 v[152:153], v[152:153], 0, s[12:13]
	v_lshl_add_u64 v[152:153], v[152:153], 0, s[12:13]
	v_lshl_add_u64 v[152:153], v[152:153], 0, s[12:13]
	v_mul_f32_e32 v128, 0xbfb8aa3b, v128
	v_mul_f32_e32 v129, 0xbfb8aa3b, v129
	v_exp_f32_e32 v128, v128
	v_exp_f32_e32 v129, v129
	v_add_f32_e32 v128, 1.0, v128
	v_add_f32_e32 v129, 1.0, v129
	v_div_scale_f32 v224, s[26:27], v128, v128, v124
	v_div_scale_f32 v229, s[26:27], v129, v129, v125
	v_rcp_f32_e32 v225, v224
	v_rcp_f32_e32 v230, v229
	v_fma_f32 v226, -v224, v225, 1.0
	v_fma_f32 v231, -v229, v230, 1.0
	v_fmac_f32_e32 v225, v226, v225
	v_fmac_f32_e32 v230, v231, v230
	v_div_scale_f32 v226, vcc, v124, v128, v124
	v_mul_f32_e32 v227, v226, v225
	v_fma_f32 v228, -v224, v227, v226
	v_fmac_f32_e32 v227, v228, v225
	v_fma_f32 v224, -v224, v227, v226
	v_div_fmas_f32 v224, v224, v225, v227
	v_div_fixup_f32 v124, v224, v128, v124
	v_div_scale_f32 v231, vcc, v125, v129, v125
	v_mul_f32_e32 v232, v231, v230
	v_fma_f32 v233, -v229, v232, v231
	v_fmac_f32_e32 v232, v233, v230
	v_fma_f32 v229, -v229, v232, v231
	v_div_fmas_f32 v229, v229, v230, v232
	v_div_fixup_f32 v125, v229, v129, v125
	v_mul_f32_e32 v130, 0xbfb8aa3b, v130
	v_mul_f32_e32 v131, 0xbfb8aa3b, v131
	v_exp_f32_e32 v130, v130
	v_exp_f32_e32 v131, v131
	v_add_f32_e32 v130, 1.0, v130
	v_add_f32_e32 v131, 1.0, v131
	v_div_scale_f32 v224, s[26:27], v130, v130, v126
	v_div_scale_f32 v229, s[26:27], v131, v131, v127
	v_rcp_f32_e32 v225, v224
	v_rcp_f32_e32 v230, v229
	v_fma_f32 v226, -v224, v225, 1.0
	v_fma_f32 v231, -v229, v230, 1.0
	v_fmac_f32_e32 v225, v226, v225
	v_fmac_f32_e32 v230, v231, v230
	v_div_scale_f32 v226, vcc, v126, v130, v126
	v_mul_f32_e32 v227, v226, v225
	v_fma_f32 v228, -v224, v227, v226
	v_fmac_f32_e32 v227, v228, v225
	v_fma_f32 v224, -v224, v227, v226
	v_div_fmas_f32 v224, v224, v225, v227
	v_div_fixup_f32 v126, v224, v130, v126
	v_div_scale_f32 v231, vcc, v127, v131, v127
	v_mul_f32_e32 v232, v231, v230
	v_fma_f32 v233, -v229, v232, v231
	v_fmac_f32_e32 v232, v233, v230
	v_fma_f32 v229, -v229, v232, v231
	v_div_fmas_f32 v229, v229, v230, v232
	v_div_fixup_f32 v127, v229, v131, v127
	v_mul_f32_e32 v60, 0xbfb8aa3b, v60
	v_mul_f32_e32 v61, 0xbfb8aa3b, v61
	v_exp_f32_e32 v60, v60
	v_exp_f32_e32 v61, v61
	v_add_f32_e32 v60, 1.0, v60
	v_add_f32_e32 v61, 1.0, v61
	v_div_scale_f32 v224, s[26:27], v60, v60, v56
	v_div_scale_f32 v229, s[26:27], v61, v61, v57
	v_rcp_f32_e32 v225, v224
	v_rcp_f32_e32 v230, v229
	v_fma_f32 v226, -v224, v225, 1.0
	v_fma_f32 v231, -v229, v230, 1.0
	v_fmac_f32_e32 v225, v226, v225
	v_fmac_f32_e32 v230, v231, v230
	v_div_scale_f32 v226, vcc, v56, v60, v56
	v_mul_f32_e32 v227, v226, v225
	v_fma_f32 v228, -v224, v227, v226
	v_fmac_f32_e32 v227, v228, v225
	v_fma_f32 v224, -v224, v227, v226
	v_div_fmas_f32 v224, v224, v225, v227
	v_div_fixup_f32 v56, v224, v60, v56
	v_div_scale_f32 v231, vcc, v57, v61, v57
	v_mul_f32_e32 v232, v231, v230
	v_fma_f32 v233, -v229, v232, v231
	v_fmac_f32_e32 v232, v233, v230
	v_fma_f32 v229, -v229, v232, v231
	v_div_fmas_f32 v229, v229, v230, v232
	v_div_fixup_f32 v57, v229, v61, v57
	v_mul_f32_e32 v62, 0xbfb8aa3b, v62
	v_mul_f32_e32 v63, 0xbfb8aa3b, v63
	v_exp_f32_e32 v62, v62
	v_exp_f32_e32 v63, v63
	v_add_f32_e32 v62, 1.0, v62
	v_add_f32_e32 v63, 1.0, v63
	v_div_scale_f32 v224, s[26:27], v62, v62, v58
	v_div_scale_f32 v229, s[26:27], v63, v63, v59
	v_rcp_f32_e32 v225, v224
	v_rcp_f32_e32 v230, v229
	v_fma_f32 v226, -v224, v225, 1.0
	v_fma_f32 v231, -v229, v230, 1.0
	v_fmac_f32_e32 v225, v226, v225
	v_fmac_f32_e32 v230, v231, v230
	v_div_scale_f32 v226, vcc, v58, v62, v58
	v_mul_f32_e32 v227, v226, v225
	v_fma_f32 v228, -v224, v227, v226
	v_fmac_f32_e32 v227, v228, v225
	v_fma_f32 v224, -v224, v227, v226
	v_div_fmas_f32 v224, v224, v225, v227
	v_div_fixup_f32 v58, v224, v62, v58
	v_div_scale_f32 v231, vcc, v59, v63, v59
	v_mul_f32_e32 v232, v231, v230
	v_fma_f32 v233, -v229, v232, v231
	v_fmac_f32_e32 v232, v233, v230
;     DI void operator()(const f32x4 (&acc)[2][2][4][2], const Unit& u, int wr, int wc, int fr, int fq) const {
;     ...
;                 for (int m = 0; m < 4; ++m) { const size_t off = (size_t)(rbase + ai * HALF + m * 16) * D + col;
;                     const f32x4 x0 = *(const f32x4*)(src + off); const f32x4 za = acc[ai][bj][m][0], zb = acc[ai][bj][m][1]; f32x4 o;
; #pragma unroll
;                     for (int q = 0; q < 4; ++q) o[q] = za[q] / (1.f + __expf(-zb[q]));
;                     *(f32x4*)(dst + off) = x0 + g0 * o; }
	v_fma_f32 v229, -v229, v232, v231
	v_div_fmas_f32 v229, v229, v230, v232
	v_div_fixup_f32 v59, v229, v63, v59
	v_mul_f32_e32 v120, 0xbfb8aa3b, v120
	v_mul_f32_e32 v121, 0xbfb8aa3b, v121
	v_exp_f32_e32 v120, v120
	v_exp_f32_e32 v121, v121
	v_add_f32_e32 v120, 1.0, v120
	v_add_f32_e32 v121, 1.0, v121
	v_div_scale_f32 v224, s[26:27], v120, v120, v116
	v_div_scale_f32 v229, s[26:27], v121, v121, v117
	v_rcp_f32_e32 v225, v224
	v_rcp_f32_e32 v230, v229
	v_fma_f32 v226, -v224, v225, 1.0
	v_fma_f32 v231, -v229, v230, 1.0
	v_fmac_f32_e32 v225, v226, v225
	v_fmac_f32_e32 v230, v231, v230
	v_div_scale_f32 v226, vcc, v116, v120, v116
	v_mul_f32_e32 v227, v226, v225
	v_fma_f32 v228, -v224, v227, v226
	v_fmac_f32_e32 v227, v228, v225
	v_fma_f32 v224, -v224, v227, v226
	v_div_fmas_f32 v224, v224, v225, v227
	v_div_fixup_f32 v116, v224, v120, v116
	v_div_scale_f32 v231, vcc, v117, v121, v117
	v_mul_f32_e32 v232, v231, v230
	v_fma_f32 v233, -v229, v232, v231
	v_fmac_f32_e32 v232, v233, v230
	v_fma_f32 v229, -v229, v232, v231
	v_div_fmas_f32 v229, v229, v230, v232
	v_div_fixup_f32 v117, v229, v121, v117
	v_mul_f32_e32 v122, 0xbfb8aa3b, v122
	v_mul_f32_e32 v123, 0xbfb8aa3b, v123
	v_exp_f32_e32 v122, v122
	v_exp_f32_e32 v123, v123
	v_add_f32_e32 v122, 1.0, v122
	v_add_f32_e32 v123, 1.0, v123
	v_div_scale_f32 v224, s[26:27], v122, v122, v118
	v_div_scale_f32 v229, s[26:27], v123, v123, v119
	v_rcp_f32_e32 v225, v224
	v_rcp_f32_e32 v230, v229
	v_fma_f32 v226, -v224, v225, 1.0
	v_fma_f32 v231, -v229, v230, 1.0
	v_fmac_f32_e32 v225, v226, v225
	v_fmac_f32_e32 v230, v231, v230
	v_div_scale_f32 v226, vcc, v118, v122, v118
	v_mul_f32_e32 v227, v226, v225
	v_fma_f32 v228, -v224, v227, v226
	v_fmac_f32_e32 v227, v228, v225
	v_fma_f32 v224, -v224, v227, v226
	v_div_fmas_f32 v224, v224, v225, v227
	v_div_fixup_f32 v118, v224, v122, v118
	v_div_scale_f32 v231, vcc, v119, v123, v119
	v_mul_f32_e32 v232, v231, v230
	v_fma_f32 v233, -v229, v232, v231
	v_fmac_f32_e32 v232, v233, v230
	v_fma_f32 v229, -v229, v232, v231
	v_div_fmas_f32 v229, v229, v230, v232
	v_div_fixup_f32 v119, v229, v123, v119
	v_mul_f32_e32 v52, 0xbfb8aa3b, v52
	v_mul_f32_e32 v53, 0xbfb8aa3b, v53
	v_exp_f32_e32 v52, v52
	v_exp_f32_e32 v53, v53
	v_add_f32_e32 v52, 1.0, v52
	v_add_f32_e32 v53, 1.0, v53
	v_div_scale_f32 v224, s[26:27], v52, v52, v48
	v_div_scale_f32 v229, s[26:27], v53, v53, v49
	v_rcp_f32_e32 v225, v224
	v_rcp_f32_e32 v230, v229
	v_fma_f32 v226, -v224, v225, 1.0
	v_fma_f32 v231, -v229, v230, 1.0
	v_fmac_f32_e32 v225, v226, v225
	v_fmac_f32_e32 v230, v231, v230
	v_div_scale_f32 v226, vcc, v48, v52, v48
	v_mul_f32_e32 v227, v226, v225
	v_fma_f32 v228, -v224, v227, v226
	v_fmac_f32_e32 v227, v228, v225
	v_fma_f32 v224, -v224, v227, v226
	v_div_fmas_f32 v224, v224, v225, v227
	v_div_fixup_f32 v48, v224, v52, v48
	v_div_scale_f32 v231, vcc, v49, v53, v49
	v_mul_f32_e32 v232, v231, v230
	v_fma_f32 v233, -v229, v232, v231
	v_fmac_f32_e32 v232, v233, v230
	v_fma_f32 v229, -v229, v232, v231
	v_div_fmas_f32 v229, v229, v230, v232
	v_div_fixup_f32 v49, v229, v53, v49
	v_mul_f32_e32 v54, 0xbfb8aa3b, v54
	v_mul_f32_e32 v55, 0xbfb8aa3b, v55
	v_exp_f32_e32 v54, v54
	v_exp_f32_e32 v55, v55
	v_add_f32_e32 v54, 1.0, v54
	v_add_f32_e32 v55, 1.0, v55
	v_div_scale_f32 v224, s[26:27], v54, v54, v50
	v_div_scale_f32 v229, s[26:27], v55, v55, v51
	v_rcp_f32_e32 v225, v224
	v_rcp_f32_e32 v230, v229
	v_fma_f32 v226, -v224, v225, 1.0
	v_fma_f32 v231, -v229, v230, 1.0
	v_fmac_f32_e32 v225, v226, v225
	v_fmac_f32_e32 v230, v231, v230
	v_div_scale_f32 v226, vcc, v50, v54, v50
	v_mul_f32_e32 v227, v226, v225
	v_fma_f32 v228, -v224, v227, v226
	v_fmac_f32_e32 v227, v228, v225
	v_fma_f32 v224, -v224, v227, v226
	v_div_fmas_f32 v224, v224, v225, v227
	v_div_fixup_f32 v50, v224, v54, v50
	v_div_scale_f32 v231, vcc, v51, v55, v51
	v_mul_f32_e32 v232, v231, v230
	v_fma_f32 v233, -v229, v232, v231
	v_fmac_f32_e32 v232, v233, v230
	v_fma_f32 v229, -v229, v232, v231
	v_div_fmas_f32 v229, v229, v230, v232
	v_div_fixup_f32 v51, v229, v55, v51
	v_mul_f32_e32 v112, 0xbfb8aa3b, v112
	v_mul_f32_e32 v113, 0xbfb8aa3b, v113
	v_exp_f32_e32 v112, v112
	v_exp_f32_e32 v113, v113
	v_add_f32_e32 v112, 1.0, v112
	v_add_f32_e32 v113, 1.0, v113
	v_div_scale_f32 v224, s[26:27], v112, v112, v108
	v_div_scale_f32 v229, s[26:27], v113, v113, v109
	v_rcp_f32_e32 v225, v224
	v_rcp_f32_e32 v230, v229
	v_fma_f32 v226, -v224, v225, 1.0
	v_fma_f32 v231, -v229, v230, 1.0
	v_fmac_f32_e32 v225, v226, v225
	v_fmac_f32_e32 v230, v231, v230
	v_div_scale_f32 v226, vcc, v108, v112, v108
	v_mul_f32_e32 v227, v226, v225
	v_fma_f32 v228, -v224, v227, v226
	v_fmac_f32_e32 v227, v228, v225
	v_fma_f32 v224, -v224, v227, v226
	v_div_fmas_f32 v224, v224, v225, v227
	v_div_fixup_f32 v108, v224, v112, v108
	v_div_scale_f32 v231, vcc, v109, v113, v109
	v_mul_f32_e32 v232, v231, v230
	v_fma_f32 v233, -v229, v232, v231
	v_fmac_f32_e32 v232, v233, v230
	v_fma_f32 v229, -v229, v232, v231
	v_div_fmas_f32 v229, v229, v230, v232
	v_div_fixup_f32 v109, v229, v113, v109
	v_mul_f32_e32 v114, 0xbfb8aa3b, v114
	v_mul_f32_e32 v115, 0xbfb8aa3b, v115
	v_exp_f32_e32 v114, v114
	v_exp_f32_e32 v115, v115
	v_add_f32_e32 v114, 1.0, v114
	v_add_f32_e32 v115, 1.0, v115
	v_div_scale_f32 v224, s[26:27], v114, v114, v110
	v_div_scale_f32 v229, s[26:27], v115, v115, v111
	v_rcp_f32_e32 v225, v224
	v_rcp_f32_e32 v230, v229
	v_fma_f32 v226, -v224, v225, 1.0
	v_fma_f32 v231, -v229, v230, 1.0
	v_fmac_f32_e32 v225, v226, v225
	v_fmac_f32_e32 v230, v231, v230
	v_div_scale_f32 v226, vcc, v110, v114, v110
	v_mul_f32_e32 v227, v226, v225
	v_fma_f32 v228, -v224, v227, v226
	v_fmac_f32_e32 v227, v228, v225
;     DI void operator()(const f32x4 (&acc)[2][2][4][2], const Unit& u, int wr, int wc, int fr, int fq) const {
;     ...
;                 for (int m = 0; m < 4; ++m) { const size_t off = (size_t)(rbase + ai * HALF + m * 16) * D + col;
;                     const f32x4 x0 = *(const f32x4*)(src + off); const f32x4 za = acc[ai][bj][m][0], zb = acc[ai][bj][m][1]; f32x4 o;
; #pragma unroll
;                     for (int q = 0; q < 4; ++q) o[q] = za[q] / (1.f + __expf(-zb[q]));
;                     *(f32x4*)(dst + off) = x0 + g0 * o; }
	v_fma_f32 v224, -v224, v227, v226
	v_div_fmas_f32 v224, v224, v225, v227
	v_div_fixup_f32 v110, v224, v114, v110
	v_div_scale_f32 v231, vcc, v111, v115, v111
	v_mul_f32_e32 v232, v231, v230
	v_fma_f32 v233, -v229, v232, v231
	v_fmac_f32_e32 v232, v233, v230
	v_fma_f32 v229, -v229, v232, v231
	v_div_fmas_f32 v229, v229, v230, v232
	v_div_fixup_f32 v111, v229, v115, v111
	v_mul_f32_e32 v44, 0xbfb8aa3b, v44
	v_mul_f32_e32 v45, 0xbfb8aa3b, v45
	v_exp_f32_e32 v44, v44
	v_exp_f32_e32 v45, v45
	v_add_f32_e32 v44, 1.0, v44
	v_add_f32_e32 v45, 1.0, v45
	v_div_scale_f32 v224, s[26:27], v44, v44, v40
	v_div_scale_f32 v229, s[26:27], v45, v45, v41
	v_rcp_f32_e32 v225, v224
	v_rcp_f32_e32 v230, v229
	v_fma_f32 v226, -v224, v225, 1.0
	v_fma_f32 v231, -v229, v230, 1.0
	v_fmac_f32_e32 v225, v226, v225
	v_fmac_f32_e32 v230, v231, v230
	v_div_scale_f32 v226, vcc, v40, v44, v40
	v_mul_f32_e32 v227, v226, v225
	v_fma_f32 v228, -v224, v227, v226
	v_fmac_f32_e32 v227, v228, v225
	v_fma_f32 v224, -v224, v227, v226
	v_div_fmas_f32 v224, v224, v225, v227
	v_div_fixup_f32 v40, v224, v44, v40
	v_div_scale_f32 v231, vcc, v41, v45, v41
	v_mul_f32_e32 v232, v231, v230
	v_fma_f32 v233, -v229, v232, v231
	v_fmac_f32_e32 v232, v233, v230
	v_fma_f32 v229, -v229, v232, v231
	v_div_fmas_f32 v229, v229, v230, v232
	v_div_fixup_f32 v41, v229, v45, v41
	v_mul_f32_e32 v46, 0xbfb8aa3b, v46
	v_mul_f32_e32 v47, 0xbfb8aa3b, v47
	v_exp_f32_e32 v46, v46
	v_exp_f32_e32 v47, v47
	v_add_f32_e32 v46, 1.0, v46
	v_add_f32_e32 v47, 1.0, v47
	v_div_scale_f32 v224, s[26:27], v46, v46, v42
	v_div_scale_f32 v229, s[26:27], v47, v47, v43
	v_rcp_f32_e32 v225, v224
	v_rcp_f32_e32 v230, v229
	v_fma_f32 v226, -v224, v225, 1.0
	v_fma_f32 v231, -v229, v230, 1.0
	v_fmac_f32_e32 v225, v226, v225
	v_fmac_f32_e32 v230, v231, v230
	v_div_scale_f32 v226, vcc, v42, v46, v42
	v_mul_f32_e32 v227, v226, v225
	v_fma_f32 v228, -v224, v227, v226
	v_fmac_f32_e32 v227, v228, v225
	v_fma_f32 v224, -v224, v227, v226
	v_div_fmas_f32 v224, v224, v225, v227
	v_div_fixup_f32 v42, v224, v46, v42
	v_div_scale_f32 v231, vcc, v43, v47, v43
	v_mul_f32_e32 v232, v231, v230
	v_fma_f32 v233, -v229, v232, v231
	v_fmac_f32_e32 v232, v233, v230
	v_fma_f32 v229, -v229, v232, v231
	v_div_fmas_f32 v229, v229, v230, v232
	v_div_fixup_f32 v43, v229, v47, v43
	v_mul_f32_e32 v104, 0xbfb8aa3b, v104
	v_mul_f32_e32 v105, 0xbfb8aa3b, v105
	v_exp_f32_e32 v104, v104
	v_exp_f32_e32 v105, v105
	v_add_f32_e32 v104, 1.0, v104
	v_add_f32_e32 v105, 1.0, v105
	v_div_scale_f32 v224, s[26:27], v104, v104, v100
	v_div_scale_f32 v229, s[26:27], v105, v105, v101
	v_rcp_f32_e32 v225, v224
	v_rcp_f32_e32 v230, v229
	v_fma_f32 v226, -v224, v225, 1.0
	v_fma_f32 v231, -v229, v230, 1.0
	v_fmac_f32_e32 v225, v226, v225
	v_fmac_f32_e32 v230, v231, v230
	v_div_scale_f32 v226, vcc, v100, v104, v100
	v_mul_f32_e32 v227, v226, v225
	v_fma_f32 v228, -v224, v227, v226
	v_fmac_f32_e32 v227, v228, v225
	v_fma_f32 v224, -v224, v227, v226
	v_div_fmas_f32 v224, v224, v225, v227
	v_div_fixup_f32 v100, v224, v104, v100
	v_div_scale_f32 v231, vcc, v101, v105, v101
	v_mul_f32_e32 v232, v231, v230
	v_fma_f32 v233, -v229, v232, v231
	v_fmac_f32_e32 v232, v233, v230
	v_fma_f32 v229, -v229, v232, v231
	v_div_fmas_f32 v229, v229, v230, v232
	v_div_fixup_f32 v101, v229, v105, v101
	v_mul_f32_e32 v106, 0xbfb8aa3b, v106
	v_mul_f32_e32 v107, 0xbfb8aa3b, v107
	v_exp_f32_e32 v106, v106
	v_exp_f32_e32 v107, v107
	v_add_f32_e32 v106, 1.0, v106
	v_add_f32_e32 v107, 1.0, v107
	v_div_scale_f32 v224, s[26:27], v106, v106, v102
	v_div_scale_f32 v229, s[26:27], v107, v107, v103
	v_rcp_f32_e32 v225, v224
	v_rcp_f32_e32 v230, v229
	v_fma_f32 v226, -v224, v225, 1.0
	v_fma_f32 v231, -v229, v230, 1.0
	v_fmac_f32_e32 v225, v226, v225
	v_fmac_f32_e32 v230, v231, v230
	v_div_scale_f32 v226, vcc, v102, v106, v102
	v_mul_f32_e32 v227, v226, v225
	v_fma_f32 v228, -v224, v227, v226
	v_fmac_f32_e32 v227, v228, v225
	v_fma_f32 v224, -v224, v227, v226
	v_div_fmas_f32 v224, v224, v225, v227
	v_div_fixup_f32 v102, v224, v106, v102
	v_div_scale_f32 v231, vcc, v103, v107, v103
	v_mul_f32_e32 v232, v231, v230
	v_fma_f32 v233, -v229, v232, v231
	v_fmac_f32_e32 v232, v233, v230
	v_fma_f32 v229, -v229, v232, v231
	v_div_fmas_f32 v229, v229, v230, v232
	v_div_fixup_f32 v103, v229, v107, v103
	v_mul_f32_e32 v36, 0xbfb8aa3b, v36
	v_mul_f32_e32 v37, 0xbfb8aa3b, v37
	v_exp_f32_e32 v36, v36
	v_exp_f32_e32 v37, v37
	v_add_f32_e32 v36, 1.0, v36
	v_add_f32_e32 v37, 1.0, v37
	v_div_scale_f32 v224, s[26:27], v36, v36, v32
	v_div_scale_f32 v229, s[26:27], v37, v37, v33
	v_rcp_f32_e32 v225, v224
	v_rcp_f32_e32 v230, v229
	v_fma_f32 v226, -v224, v225, 1.0
	v_fma_f32 v231, -v229, v230, 1.0
	v_fmac_f32_e32 v225, v226, v225
	v_fmac_f32_e32 v230, v231, v230
	v_div_scale_f32 v226, vcc, v32, v36, v32
	v_mul_f32_e32 v227, v226, v225
	v_fma_f32 v228, -v224, v227, v226
	v_fmac_f32_e32 v227, v228, v225
	v_fma_f32 v224, -v224, v227, v226
	v_div_fmas_f32 v224, v224, v225, v227
	v_div_fixup_f32 v32, v224, v36, v32
	v_div_scale_f32 v231, vcc, v33, v37, v33
	v_mul_f32_e32 v232, v231, v230
	v_fma_f32 v233, -v229, v232, v231
	v_fmac_f32_e32 v232, v233, v230
	v_fma_f32 v229, -v229, v232, v231
	v_div_fmas_f32 v229, v229, v230, v232
	v_div_fixup_f32 v33, v229, v37, v33
	v_mul_f32_e32 v38, 0xbfb8aa3b, v38
	v_mul_f32_e32 v39, 0xbfb8aa3b, v39
	v_exp_f32_e32 v38, v38
	v_exp_f32_e32 v39, v39
	v_add_f32_e32 v38, 1.0, v38
	v_add_f32_e32 v39, 1.0, v39
	v_div_scale_f32 v224, s[26:27], v38, v38, v34
	v_div_scale_f32 v229, s[26:27], v39, v39, v35
	v_rcp_f32_e32 v225, v224
	v_rcp_f32_e32 v230, v229
	v_fma_f32 v226, -v224, v225, 1.0
	v_fma_f32 v231, -v229, v230, 1.0
;     DI void operator()(const f32x4 (&acc)[2][2][4][2], const Unit& u, int wr, int wc, int fr, int fq) const {
;     ...
;                 for (int m = 0; m < 4; ++m) { const size_t off = (size_t)(rbase + ai * HALF + m * 16) * D + col;
;                     const f32x4 x0 = *(const f32x4*)(src + off); const f32x4 za = acc[ai][bj][m][0], zb = acc[ai][bj][m][1]; f32x4 o;
; #pragma unroll
;                     for (int q = 0; q < 4; ++q) o[q] = za[q] / (1.f + __expf(-zb[q]));
;                     *(f32x4*)(dst + off) = x0 + g0 * o; }
	v_fmac_f32_e32 v225, v226, v225
	v_fmac_f32_e32 v230, v231, v230
	v_div_scale_f32 v226, vcc, v34, v38, v34
	v_mul_f32_e32 v227, v226, v225
	v_fma_f32 v228, -v224, v227, v226
	v_fmac_f32_e32 v227, v228, v225
	v_fma_f32 v224, -v224, v227, v226
	v_div_fmas_f32 v224, v224, v225, v227
	v_div_fixup_f32 v34, v224, v38, v34
	v_div_scale_f32 v231, vcc, v35, v39, v35
	v_mul_f32_e32 v232, v231, v230
	v_fma_f32 v233, -v229, v232, v231
	v_fmac_f32_e32 v232, v233, v230
	v_fma_f32 v229, -v229, v232, v231
	v_div_fmas_f32 v229, v229, v230, v232
	v_div_fixup_f32 v35, v229, v39, v35
	global_load_dwordx4 v[128:131], v[152:153], off
	global_load_dwordx4 v[60:63], v[152:153], off offset:256
	v_lshl_add_u64 v[152:153], v[152:153], 0, s[12:13]
	global_load_dwordx4 v[120:123], v[152:153], off
	global_load_dwordx4 v[52:55], v[152:153], off offset:256
	v_lshl_add_u64 v[152:153], v[152:153], 0, s[12:13]
	global_load_dwordx4 v[112:115], v[152:153], off
	global_load_dwordx4 v[44:47], v[152:153], off offset:256
	v_lshl_add_u64 v[152:153], v[152:153], 0, s[12:13]
	global_load_dwordx4 v[104:107], v[152:153], off
	global_load_dwordx4 v[36:39], v[152:153], off offset:256
	v_mul_f32_e32 v96, 0xbfb8aa3b, v96
	v_mul_f32_e32 v97, 0xbfb8aa3b, v97
	v_exp_f32_e32 v96, v96
	v_exp_f32_e32 v97, v97
	v_add_f32_e32 v96, 1.0, v96
	v_add_f32_e32 v97, 1.0, v97
	v_div_scale_f32 v224, s[26:27], v96, v96, v92
	v_div_scale_f32 v229, s[26:27], v97, v97, v93
	v_rcp_f32_e32 v225, v224
	v_rcp_f32_e32 v230, v229
	v_fma_f32 v226, -v224, v225, 1.0
	v_fma_f32 v231, -v229, v230, 1.0
	v_fmac_f32_e32 v225, v226, v225
	v_fmac_f32_e32 v230, v231, v230
	v_div_scale_f32 v226, vcc, v92, v96, v92
	v_mul_f32_e32 v227, v226, v225
	v_fma_f32 v228, -v224, v227, v226
	v_fmac_f32_e32 v227, v228, v225
	v_fma_f32 v224, -v224, v227, v226
	v_div_fmas_f32 v224, v224, v225, v227
	v_div_fixup_f32 v92, v224, v96, v92
	v_div_scale_f32 v231, vcc, v93, v97, v93
	v_mul_f32_e32 v232, v231, v230
	v_fma_f32 v233, -v229, v232, v231
	v_fmac_f32_e32 v232, v233, v230
	v_fma_f32 v229, -v229, v232, v231
	v_div_fmas_f32 v229, v229, v230, v232
	v_div_fixup_f32 v93, v229, v97, v93
	v_mul_f32_e32 v98, 0xbfb8aa3b, v98
	v_mul_f32_e32 v99, 0xbfb8aa3b, v99
	v_exp_f32_e32 v98, v98
	v_exp_f32_e32 v99, v99
	v_add_f32_e32 v98, 1.0, v98
	v_add_f32_e32 v99, 1.0, v99
	v_div_scale_f32 v224, s[26:27], v98, v98, v94
	v_div_scale_f32 v229, s[26:27], v99, v99, v95
	v_rcp_f32_e32 v225, v224
	v_rcp_f32_e32 v230, v229
	v_fma_f32 v226, -v224, v225, 1.0
	v_fma_f32 v231, -v229, v230, 1.0
	v_fmac_f32_e32 v225, v226, v225
	v_fmac_f32_e32 v230, v231, v230
	v_div_scale_f32 v226, vcc, v94, v98, v94
	v_mul_f32_e32 v227, v226, v225
	v_fma_f32 v228, -v224, v227, v226
	v_fmac_f32_e32 v227, v228, v225
	v_fma_f32 v224, -v224, v227, v226
	v_div_fmas_f32 v224, v224, v225, v227
	v_div_fixup_f32 v94, v224, v98, v94
	v_div_scale_f32 v231, vcc, v95, v99, v95
	v_mul_f32_e32 v232, v231, v230
	v_fma_f32 v233, -v229, v232, v231
	v_fmac_f32_e32 v232, v233, v230
	v_fma_f32 v229, -v229, v232, v231
	v_div_fmas_f32 v229, v229, v230, v232
	v_div_fixup_f32 v95, v229, v99, v95
	v_mul_f32_e32 v28, 0xbfb8aa3b, v28
	v_mul_f32_e32 v29, 0xbfb8aa3b, v29
	v_exp_f32_e32 v28, v28
	v_exp_f32_e32 v29, v29
	v_add_f32_e32 v28, 1.0, v28
	v_add_f32_e32 v29, 1.0, v29
	v_div_scale_f32 v224, s[26:27], v28, v28, v24
	v_div_scale_f32 v229, s[26:27], v29, v29, v25
	v_rcp_f32_e32 v225, v224
	v_rcp_f32_e32 v230, v229
	v_fma_f32 v226, -v224, v225, 1.0
	v_fma_f32 v231, -v229, v230, 1.0
	v_fmac_f32_e32 v225, v226, v225
	v_fmac_f32_e32 v230, v231, v230
	v_div_scale_f32 v226, vcc, v24, v28, v24
	v_mul_f32_e32 v227, v226, v225
	v_fma_f32 v228, -v224, v227, v226
	v_fmac_f32_e32 v227, v228, v225
	v_fma_f32 v224, -v224, v227, v226
	v_div_fmas_f32 v224, v224, v225, v227
	v_div_fixup_f32 v24, v224, v28, v24
	v_div_scale_f32 v231, vcc, v25, v29, v25
	v_mul_f32_e32 v232, v231, v230
	v_fma_f32 v233, -v229, v232, v231
	v_fmac_f32_e32 v232, v233, v230
	v_fma_f32 v229, -v229, v232, v231
	v_div_fmas_f32 v229, v229, v230, v232
	v_div_fixup_f32 v25, v229, v29, v25
	v_mul_f32_e32 v30, 0xbfb8aa3b, v30
	v_mul_f32_e32 v31, 0xbfb8aa3b, v31
	v_exp_f32_e32 v30, v30
	v_exp_f32_e32 v31, v31
	v_add_f32_e32 v30, 1.0, v30
	v_add_f32_e32 v31, 1.0, v31
	v_div_scale_f32 v224, s[26:27], v30, v30, v26
	v_div_scale_f32 v229, s[26:27], v31, v31, v27
	v_rcp_f32_e32 v225, v224
	v_rcp_f32_e32 v230, v229
	v_fma_f32 v226, -v224, v225, 1.0
	v_fma_f32 v231, -v229, v230, 1.0
	v_fmac_f32_e32 v225, v226, v225
	v_fmac_f32_e32 v230, v231, v230
	v_div_scale_f32 v226, vcc, v26, v30, v26
	v_mul_f32_e32 v227, v226, v225
	v_fma_f32 v228, -v224, v227, v226
	v_fmac_f32_e32 v227, v228, v225
	v_fma_f32 v224, -v224, v227, v226
	v_div_fmas_f32 v224, v224, v225, v227
	v_div_fixup_f32 v26, v224, v30, v26
	v_div_scale_f32 v231, vcc, v27, v31, v27
	v_mul_f32_e32 v232, v231, v230
	v_fma_f32 v233, -v229, v232, v231
	v_fmac_f32_e32 v232, v233, v230
	v_fma_f32 v229, -v229, v232, v231
	v_div_fmas_f32 v229, v229, v230, v232
	v_div_fixup_f32 v27, v229, v31, v27
	v_mul_f32_e32 v88, 0xbfb8aa3b, v88
	v_mul_f32_e32 v89, 0xbfb8aa3b, v89
	v_exp_f32_e32 v88, v88
	v_exp_f32_e32 v89, v89
	v_add_f32_e32 v88, 1.0, v88
	v_add_f32_e32 v89, 1.0, v89
	v_div_scale_f32 v224, s[26:27], v88, v88, v80
	v_div_scale_f32 v229, s[26:27], v89, v89, v81
	v_rcp_f32_e32 v225, v224
	v_rcp_f32_e32 v230, v229
	v_fma_f32 v226, -v224, v225, 1.0
	v_fma_f32 v231, -v229, v230, 1.0
	v_fmac_f32_e32 v225, v226, v225
	v_fmac_f32_e32 v230, v231, v230
	v_div_scale_f32 v226, vcc, v80, v88, v80
	v_mul_f32_e32 v227, v226, v225
	v_fma_f32 v228, -v224, v227, v226
	v_fmac_f32_e32 v227, v228, v225
	v_fma_f32 v224, -v224, v227, v226
;     DI void operator()(const f32x4 (&acc)[2][2][4][2], const Unit& u, int wr, int wc, int fr, int fq) const {
;     ...
;                 for (int m = 0; m < 4; ++m) { const size_t off = (size_t)(rbase + ai * HALF + m * 16) * D + col;
;                     const f32x4 x0 = *(const f32x4*)(src + off); const f32x4 za = acc[ai][bj][m][0], zb = acc[ai][bj][m][1]; f32x4 o;
; #pragma unroll
;                     for (int q = 0; q < 4; ++q) o[q] = za[q] / (1.f + __expf(-zb[q]));
;                     *(f32x4*)(dst + off) = x0 + g0 * o; }
	v_div_fmas_f32 v224, v224, v225, v227
	v_div_fixup_f32 v80, v224, v88, v80
	v_div_scale_f32 v231, vcc, v81, v89, v81
	v_mul_f32_e32 v232, v231, v230
	v_fma_f32 v233, -v229, v232, v231
	v_fmac_f32_e32 v232, v233, v230
	v_fma_f32 v229, -v229, v232, v231
	v_div_fmas_f32 v229, v229, v230, v232
	v_div_fixup_f32 v81, v229, v89, v81
	v_mul_f32_e32 v90, 0xbfb8aa3b, v90
	v_mul_f32_e32 v91, 0xbfb8aa3b, v91
	v_exp_f32_e32 v90, v90
	v_exp_f32_e32 v91, v91
	v_add_f32_e32 v90, 1.0, v90
	v_add_f32_e32 v91, 1.0, v91
	v_div_scale_f32 v224, s[26:27], v90, v90, v82
	v_div_scale_f32 v229, s[26:27], v91, v91, v83
	v_rcp_f32_e32 v225, v224
	v_rcp_f32_e32 v230, v229
	v_fma_f32 v226, -v224, v225, 1.0
	v_fma_f32 v231, -v229, v230, 1.0
	v_fmac_f32_e32 v225, v226, v225
	v_fmac_f32_e32 v230, v231, v230
	v_div_scale_f32 v226, vcc, v82, v90, v82
	v_mul_f32_e32 v227, v226, v225
	v_fma_f32 v228, -v224, v227, v226
	v_fmac_f32_e32 v227, v228, v225
	v_fma_f32 v224, -v224, v227, v226
	v_div_fmas_f32 v224, v224, v225, v227
	v_div_fixup_f32 v82, v224, v90, v82
	v_div_scale_f32 v231, vcc, v83, v91, v83
	v_mul_f32_e32 v232, v231, v230
	v_fma_f32 v233, -v229, v232, v231
	v_fmac_f32_e32 v232, v233, v230
	v_fma_f32 v229, -v229, v232, v231
	v_div_fmas_f32 v229, v229, v230, v232
	v_div_fixup_f32 v83, v229, v91, v83
	v_mul_f32_e32 v20, 0xbfb8aa3b, v20
	v_mul_f32_e32 v21, 0xbfb8aa3b, v21
	v_exp_f32_e32 v20, v20
	v_exp_f32_e32 v21, v21
	v_add_f32_e32 v20, 1.0, v20
	v_add_f32_e32 v21, 1.0, v21
	v_div_scale_f32 v224, s[26:27], v20, v20, v16
	v_div_scale_f32 v229, s[26:27], v21, v21, v17
	v_rcp_f32_e32 v225, v224
	v_rcp_f32_e32 v230, v229
	v_fma_f32 v226, -v224, v225, 1.0
	v_fma_f32 v231, -v229, v230, 1.0
	v_fmac_f32_e32 v225, v226, v225
	v_fmac_f32_e32 v230, v231, v230
	v_div_scale_f32 v226, vcc, v16, v20, v16
	v_mul_f32_e32 v227, v226, v225
	v_fma_f32 v228, -v224, v227, v226
	v_fmac_f32_e32 v227, v228, v225
	v_fma_f32 v224, -v224, v227, v226
	v_div_fmas_f32 v224, v224, v225, v227
	v_div_fixup_f32 v16, v224, v20, v16
	v_div_scale_f32 v231, vcc, v17, v21, v17
	v_mul_f32_e32 v232, v231, v230
	v_fma_f32 v233, -v229, v232, v231
	v_fmac_f32_e32 v232, v233, v230
	v_fma_f32 v229, -v229, v232, v231
	v_div_fmas_f32 v229, v229, v230, v232
	v_div_fixup_f32 v17, v229, v21, v17
	v_mul_f32_e32 v22, 0xbfb8aa3b, v22
	v_mul_f32_e32 v23, 0xbfb8aa3b, v23
	v_exp_f32_e32 v22, v22
	v_exp_f32_e32 v23, v23
	v_add_f32_e32 v22, 1.0, v22
	v_add_f32_e32 v23, 1.0, v23
	v_div_scale_f32 v224, s[26:27], v22, v22, v18
	v_div_scale_f32 v229, s[26:27], v23, v23, v19
	v_rcp_f32_e32 v225, v224
	v_rcp_f32_e32 v230, v229
	v_fma_f32 v226, -v224, v225, 1.0
	v_fma_f32 v231, -v229, v230, 1.0
	v_fmac_f32_e32 v225, v226, v225
	v_fmac_f32_e32 v230, v231, v230
	v_div_scale_f32 v226, vcc, v18, v22, v18
	v_mul_f32_e32 v227, v226, v225
	v_fma_f32 v228, -v224, v227, v226
	v_fmac_f32_e32 v227, v228, v225
	v_fma_f32 v224, -v224, v227, v226
	v_div_fmas_f32 v224, v224, v225, v227
	v_div_fixup_f32 v18, v224, v22, v18
	v_div_scale_f32 v231, vcc, v19, v23, v19
	v_mul_f32_e32 v232, v231, v230
	v_fma_f32 v233, -v229, v232, v231
	v_fmac_f32_e32 v232, v233, v230
	v_fma_f32 v229, -v229, v232, v231
	v_div_fmas_f32 v229, v229, v230, v232
	v_div_fixup_f32 v19, v229, v23, v19
	v_mul_f32_e32 v76, 0xbfb8aa3b, v76
	v_mul_f32_e32 v77, 0xbfb8aa3b, v77
	v_exp_f32_e32 v76, v76
	v_exp_f32_e32 v77, v77
	v_add_f32_e32 v76, 1.0, v76
	v_add_f32_e32 v77, 1.0, v77
	v_div_scale_f32 v224, s[26:27], v76, v76, v72
	v_div_scale_f32 v229, s[26:27], v77, v77, v73
	v_rcp_f32_e32 v225, v224
	v_rcp_f32_e32 v230, v229
	v_fma_f32 v226, -v224, v225, 1.0
	v_fma_f32 v231, -v229, v230, 1.0
	v_fmac_f32_e32 v225, v226, v225
	v_fmac_f32_e32 v230, v231, v230
	v_div_scale_f32 v226, vcc, v72, v76, v72
	v_mul_f32_e32 v227, v226, v225
	v_fma_f32 v228, -v224, v227, v226
	v_fmac_f32_e32 v227, v228, v225
	v_fma_f32 v224, -v224, v227, v226
	v_div_fmas_f32 v224, v224, v225, v227
	v_div_fixup_f32 v72, v224, v76, v72
	v_div_scale_f32 v231, vcc, v73, v77, v73
	v_mul_f32_e32 v232, v231, v230
	v_fma_f32 v233, -v229, v232, v231
	v_fmac_f32_e32 v232, v233, v230
	v_fma_f32 v229, -v229, v232, v231
	v_div_fmas_f32 v229, v229, v230, v232
	v_div_fixup_f32 v73, v229, v77, v73
	v_mul_f32_e32 v78, 0xbfb8aa3b, v78
	v_mul_f32_e32 v79, 0xbfb8aa3b, v79
	v_exp_f32_e32 v78, v78
	v_exp_f32_e32 v79, v79
	v_add_f32_e32 v78, 1.0, v78
	v_add_f32_e32 v79, 1.0, v79
	v_div_scale_f32 v224, s[26:27], v78, v78, v74
	v_div_scale_f32 v229, s[26:27], v79, v79, v75
	v_rcp_f32_e32 v225, v224
	v_rcp_f32_e32 v230, v229
	v_fma_f32 v226, -v224, v225, 1.0
	v_fma_f32 v231, -v229, v230, 1.0
	v_fmac_f32_e32 v225, v226, v225
	v_fmac_f32_e32 v230, v231, v230
	v_div_scale_f32 v226, vcc, v74, v78, v74
	v_mul_f32_e32 v227, v226, v225
	v_fma_f32 v228, -v224, v227, v226
	v_fmac_f32_e32 v227, v228, v225
	v_fma_f32 v224, -v224, v227, v226
	v_div_fmas_f32 v224, v224, v225, v227
	v_div_fixup_f32 v74, v224, v78, v74
	v_div_scale_f32 v231, vcc, v75, v79, v75
	v_mul_f32_e32 v232, v231, v230
	v_fma_f32 v233, -v229, v232, v231
	v_fmac_f32_e32 v232, v233, v230
	v_fma_f32 v229, -v229, v232, v231
	v_div_fmas_f32 v229, v229, v230, v232
	v_div_fixup_f32 v75, v229, v79, v75
	v_mul_f32_e32 v12, 0xbfb8aa3b, v12
	v_mul_f32_e32 v13, 0xbfb8aa3b, v13
	v_exp_f32_e32 v12, v12
	v_exp_f32_e32 v13, v13
	v_add_f32_e32 v12, 1.0, v12
	v_add_f32_e32 v13, 1.0, v13
	v_div_scale_f32 v224, s[26:27], v12, v12, v8
	v_div_scale_f32 v229, s[26:27], v13, v13, v9
	v_rcp_f32_e32 v225, v224
	v_rcp_f32_e32 v230, v229
	v_fma_f32 v226, -v224, v225, 1.0
	v_fma_f32 v231, -v229, v230, 1.0
	v_fmac_f32_e32 v225, v226, v225
	v_fmac_f32_e32 v230, v231, v230
	v_div_scale_f32 v226, vcc, v8, v12, v8
;     DI void operator()(const f32x4 (&acc)[2][2][4][2], const Unit& u, int wr, int wc, int fr, int fq) const {
;     ...
;                 for (int m = 0; m < 4; ++m) { const size_t off = (size_t)(rbase + ai * HALF + m * 16) * D + col;
;                     const f32x4 x0 = *(const f32x4*)(src + off); const f32x4 za = acc[ai][bj][m][0], zb = acc[ai][bj][m][1]; f32x4 o;
; #pragma unroll
;                     for (int q = 0; q < 4; ++q) o[q] = za[q] / (1.f + __expf(-zb[q]));
;                     *(f32x4*)(dst + off) = x0 + g0 * o; }
	v_mul_f32_e32 v227, v226, v225
	v_fma_f32 v228, -v224, v227, v226
	v_fmac_f32_e32 v227, v228, v225
	v_fma_f32 v224, -v224, v227, v226
	v_div_fmas_f32 v224, v224, v225, v227
	v_div_fixup_f32 v8, v224, v12, v8
	v_div_scale_f32 v231, vcc, v9, v13, v9
	v_mul_f32_e32 v232, v231, v230
	v_fma_f32 v233, -v229, v232, v231
	v_fmac_f32_e32 v232, v233, v230
	v_fma_f32 v229, -v229, v232, v231
	v_div_fmas_f32 v229, v229, v230, v232
	v_div_fixup_f32 v9, v229, v13, v9
	v_mul_f32_e32 v14, 0xbfb8aa3b, v14
	v_mul_f32_e32 v15, 0xbfb8aa3b, v15
	v_exp_f32_e32 v14, v14
	v_exp_f32_e32 v15, v15
	v_add_f32_e32 v14, 1.0, v14
	v_add_f32_e32 v15, 1.0, v15
	v_div_scale_f32 v224, s[26:27], v14, v14, v10
	v_div_scale_f32 v229, s[26:27], v15, v15, v11
	v_rcp_f32_e32 v225, v224
	v_rcp_f32_e32 v230, v229
	v_fma_f32 v226, -v224, v225, 1.0
	v_fma_f32 v231, -v229, v230, 1.0
	v_fmac_f32_e32 v225, v226, v225
	v_fmac_f32_e32 v230, v231, v230
	v_div_scale_f32 v226, vcc, v10, v14, v10
	v_mul_f32_e32 v227, v226, v225
	v_fma_f32 v228, -v224, v227, v226
	v_fmac_f32_e32 v227, v228, v225
	v_fma_f32 v224, -v224, v227, v226
	v_div_fmas_f32 v224, v224, v225, v227
	v_div_fixup_f32 v10, v224, v14, v10
	v_div_scale_f32 v231, vcc, v11, v15, v11
	v_mul_f32_e32 v232, v231, v230
	v_fma_f32 v233, -v229, v232, v231
	v_fmac_f32_e32 v232, v233, v230
	v_fma_f32 v229, -v229, v232, v231
	v_div_fmas_f32 v229, v229, v230, v232
	v_div_fixup_f32 v11, v229, v15, v11
	v_mul_f32_e32 v68, 0xbfb8aa3b, v68
	v_mul_f32_e32 v69, 0xbfb8aa3b, v69
	v_exp_f32_e32 v68, v68
	v_exp_f32_e32 v69, v69
	v_add_f32_e32 v68, 1.0, v68
	v_add_f32_e32 v69, 1.0, v69
	v_div_scale_f32 v224, s[26:27], v68, v68, v64
	v_div_scale_f32 v229, s[26:27], v69, v69, v65
	v_rcp_f32_e32 v225, v224
	v_rcp_f32_e32 v230, v229
	v_fma_f32 v226, -v224, v225, 1.0
	v_fma_f32 v231, -v229, v230, 1.0
	v_fmac_f32_e32 v225, v226, v225
	v_fmac_f32_e32 v230, v231, v230
	v_div_scale_f32 v226, vcc, v64, v68, v64
	v_mul_f32_e32 v227, v226, v225
	v_fma_f32 v228, -v224, v227, v226
	v_fmac_f32_e32 v227, v228, v225
	v_fma_f32 v224, -v224, v227, v226
	v_div_fmas_f32 v224, v224, v225, v227
	v_div_fixup_f32 v64, v224, v68, v64
	v_div_scale_f32 v231, vcc, v65, v69, v65
	v_mul_f32_e32 v232, v231, v230
	v_fma_f32 v233, -v229, v232, v231
	v_fmac_f32_e32 v232, v233, v230
	v_fma_f32 v229, -v229, v232, v231
	v_div_fmas_f32 v229, v229, v230, v232
	v_div_fixup_f32 v65, v229, v69, v65
	v_mul_f32_e32 v70, 0xbfb8aa3b, v70
	v_mul_f32_e32 v71, 0xbfb8aa3b, v71
	v_exp_f32_e32 v70, v70
	v_exp_f32_e32 v71, v71
	v_add_f32_e32 v70, 1.0, v70
	v_add_f32_e32 v71, 1.0, v71
	v_div_scale_f32 v224, s[26:27], v70, v70, v66
	v_div_scale_f32 v229, s[26:27], v71, v71, v67
	v_rcp_f32_e32 v225, v224
	v_rcp_f32_e32 v230, v229
	v_fma_f32 v226, -v224, v225, 1.0
	v_fma_f32 v231, -v229, v230, 1.0
	v_fmac_f32_e32 v225, v226, v225
	v_fmac_f32_e32 v230, v231, v230
	v_div_scale_f32 v226, vcc, v66, v70, v66
	v_mul_f32_e32 v227, v226, v225
	v_fma_f32 v228, -v224, v227, v226
	v_fmac_f32_e32 v227, v228, v225
	v_fma_f32 v224, -v224, v227, v226
	v_div_fmas_f32 v224, v224, v225, v227
	v_div_fixup_f32 v66, v224, v70, v66
	v_div_scale_f32 v231, vcc, v67, v71, v67
	v_mul_f32_e32 v232, v231, v230
	v_fma_f32 v233, -v229, v232, v231
	v_fmac_f32_e32 v232, v233, v230
	v_fma_f32 v229, -v229, v232, v231
	v_div_fmas_f32 v229, v229, v230, v232
	v_div_fixup_f32 v67, v229, v71, v67
	v_mul_f32_e32 v4, 0xbfb8aa3b, v4
	v_mul_f32_e32 v5, 0xbfb8aa3b, v5
	v_exp_f32_e32 v4, v4
	v_exp_f32_e32 v5, v5
	v_add_f32_e32 v4, 1.0, v4
	v_add_f32_e32 v5, 1.0, v5
	v_div_scale_f32 v224, s[26:27], v4, v4, v0
	v_div_scale_f32 v229, s[26:27], v5, v5, v1
	v_rcp_f32_e32 v225, v224
	v_rcp_f32_e32 v230, v229
	v_fma_f32 v226, -v224, v225, 1.0
	v_fma_f32 v231, -v229, v230, 1.0
	v_fmac_f32_e32 v225, v226, v225
	v_fmac_f32_e32 v230, v231, v230
	v_div_scale_f32 v226, vcc, v0, v4, v0
	v_mul_f32_e32 v227, v226, v225
	v_fma_f32 v228, -v224, v227, v226
	v_fmac_f32_e32 v227, v228, v225
	v_fma_f32 v224, -v224, v227, v226
	v_div_fmas_f32 v224, v224, v225, v227
	v_div_fixup_f32 v0, v224, v4, v0
	v_div_scale_f32 v231, vcc, v1, v5, v1
	v_mul_f32_e32 v232, v231, v230
	v_fma_f32 v233, -v229, v232, v231
	v_fmac_f32_e32 v232, v233, v230
	v_fma_f32 v229, -v229, v232, v231
	v_div_fmas_f32 v229, v229, v230, v232
	v_div_fixup_f32 v1, v229, v5, v1
	v_mul_f32_e32 v6, 0xbfb8aa3b, v6
	v_mul_f32_e32 v7, 0xbfb8aa3b, v7
	v_exp_f32_e32 v6, v6
	v_exp_f32_e32 v7, v7
	v_add_f32_e32 v6, 1.0, v6
	v_add_f32_e32 v7, 1.0, v7
	v_div_scale_f32 v224, s[26:27], v6, v6, v2
	v_div_scale_f32 v229, s[26:27], v7, v7, v3
	v_rcp_f32_e32 v225, v224
	v_rcp_f32_e32 v230, v229
	v_fma_f32 v226, -v224, v225, 1.0
	v_fma_f32 v231, -v229, v230, 1.0
	v_fmac_f32_e32 v225, v226, v225
	v_fmac_f32_e32 v230, v231, v230
	v_div_scale_f32 v226, vcc, v2, v6, v2
	v_mul_f32_e32 v227, v226, v225
	v_fma_f32 v228, -v224, v227, v226
	v_fmac_f32_e32 v227, v228, v225
	v_fma_f32 v224, -v224, v227, v226
	v_div_fmas_f32 v224, v224, v225, v227
	v_div_fixup_f32 v2, v224, v6, v2
	v_div_scale_f32 v231, vcc, v3, v7, v3
	v_mul_f32_e32 v232, v231, v230
	v_fma_f32 v233, -v229, v232, v231
	v_fmac_f32_e32 v232, v233, v230
	v_fma_f32 v229, -v229, v232, v231
	v_div_fmas_f32 v229, v229, v230, v232
	v_div_fixup_f32 v3, v229, v7, v3
	s_waitcnt vmcnt(15)
;     DI void operator()(const f32x4 (&acc)[2][2][4][2], const Unit& u, int wr, int wc, int fr, int fq) const {
;     ...
;                 for (int m = 0; m < 4; ++m) { const size_t off = (size_t)(rbase + ai * HALF + m * 16) * D + col;
;                     const f32x4 x0 = *(const f32x4*)(src + off); const f32x4 za = acc[ai][bj][m][0], zb = acc[ai][bj][m][1]; f32x4 o;
; #pragma unroll
;                     for (int q = 0; q < 4; ++q) o[q] = za[q] / (1.f + __expf(-zb[q]));
;                     *(f32x4*)(dst + off) = x0 + g0 * o; }
	v_pk_fma_f32 v[124:125], v[124:125], v[216:217], v[176:177]
	v_pk_fma_f32 v[126:127], v[126:127], v[218:219], v[178:179]
	global_store_dwordx4 v[234:235], v[124:127], off
	s_waitcnt vmcnt(15)
	v_pk_fma_f32 v[56:57], v[56:57], v[220:221], v[180:181]
	v_pk_fma_f32 v[58:59], v[58:59], v[222:223], v[182:183]
	global_store_dwordx4 v[234:235], v[56:59], off offset:256
	v_lshl_add_u64 v[234:235], v[234:235], 0, s[12:13]
	s_waitcnt vmcnt(15)
	v_pk_fma_f32 v[116:117], v[116:117], v[216:217], v[184:185]
	v_pk_fma_f32 v[118:119], v[118:119], v[218:219], v[186:187]
	global_store_dwordx4 v[234:235], v[116:119], off
	s_waitcnt vmcnt(15)
	v_pk_fma_f32 v[48:49], v[48:49], v[220:221], v[188:189]
	v_pk_fma_f32 v[50:51], v[50:51], v[222:223], v[190:191]
	global_store_dwordx4 v[234:235], v[48:51], off offset:256
	v_lshl_add_u64 v[234:235], v[234:235], 0, s[12:13]
	s_waitcnt vmcnt(15)
	v_pk_fma_f32 v[108:109], v[108:109], v[216:217], v[192:193]
	v_pk_fma_f32 v[110:111], v[110:111], v[218:219], v[194:195]
	global_store_dwordx4 v[234:235], v[108:111], off
	s_waitcnt vmcnt(15)
	v_pk_fma_f32 v[40:41], v[40:41], v[220:221], v[196:197]
	v_pk_fma_f32 v[42:43], v[42:43], v[222:223], v[198:199]
	global_store_dwordx4 v[234:235], v[40:43], off offset:256
	v_lshl_add_u64 v[234:235], v[234:235], 0, s[12:13]
	s_waitcnt vmcnt(15)
	v_pk_fma_f32 v[100:101], v[100:101], v[216:217], v[200:201]
	v_pk_fma_f32 v[102:103], v[102:103], v[218:219], v[202:203]
	global_store_dwordx4 v[234:235], v[100:103], off
	s_waitcnt vmcnt(15)
	v_pk_fma_f32 v[32:33], v[32:33], v[220:221], v[204:205]
	v_pk_fma_f32 v[34:35], v[34:35], v[222:223], v[206:207]
	global_store_dwordx4 v[234:235], v[32:35], off offset:256
	v_lshl_add_u64 v[234:235], v[234:235], 0, s[12:13]
	v_lshl_add_u64 v[234:235], v[234:235], 0, s[12:13]
	v_lshl_add_u64 v[234:235], v[234:235], 0, s[12:13]
	v_lshl_add_u64 v[234:235], v[234:235], 0, s[12:13]
	v_lshl_add_u64 v[234:235], v[234:235], 0, s[12:13]
	s_waitcnt vmcnt(15)
	v_pk_fma_f32 v[92:93], v[92:93], v[216:217], v[128:129]
	v_pk_fma_f32 v[94:95], v[94:95], v[218:219], v[130:131]
	global_store_dwordx4 v[234:235], v[92:95], off
	s_waitcnt vmcnt(15)
	v_pk_fma_f32 v[24:25], v[24:25], v[220:221], v[60:61]
	v_pk_fma_f32 v[26:27], v[26:27], v[222:223], v[62:63]
	global_store_dwordx4 v[234:235], v[24:27], off offset:256
	v_lshl_add_u64 v[234:235], v[234:235], 0, s[12:13]
	s_waitcnt vmcnt(15)
	v_pk_fma_f32 v[80:81], v[80:81], v[216:217], v[120:121]
	v_pk_fma_f32 v[82:83], v[82:83], v[218:219], v[122:123]
	global_store_dwordx4 v[234:235], v[80:83], off
	s_waitcnt vmcnt(15)
	v_pk_fma_f32 v[16:17], v[16:17], v[220:221], v[52:53]
	v_pk_fma_f32 v[18:19], v[18:19], v[222:223], v[54:55]
	global_store_dwordx4 v[234:235], v[16:19], off offset:256
	v_lshl_add_u64 v[234:235], v[234:235], 0, s[12:13]
	s_waitcnt vmcnt(15)
	v_pk_fma_f32 v[72:73], v[72:73], v[216:217], v[112:113]
	v_pk_fma_f32 v[74:75], v[74:75], v[218:219], v[114:115]
	global_store_dwordx4 v[234:235], v[72:75], off
	s_waitcnt vmcnt(15)
	v_pk_fma_f32 v[8:9], v[8:9], v[220:221], v[44:45]
	v_pk_fma_f32 v[10:11], v[10:11], v[222:223], v[46:47]
	global_store_dwordx4 v[234:235], v[8:11], off offset:256
	v_lshl_add_u64 v[234:235], v[234:235], 0, s[12:13]
	s_waitcnt vmcnt(15)
	v_pk_fma_f32 v[64:65], v[64:65], v[216:217], v[104:105]
	v_pk_fma_f32 v[66:67], v[66:67], v[218:219], v[106:107]
	global_store_dwordx4 v[234:235], v[64:67], off
	s_waitcnt vmcnt(15)
	v_pk_fma_f32 v[0:1], v[0:1], v[220:221], v[36:37]
	v_pk_fma_f32 v[2:3], v[2:3], v[222:223], v[38:39]
	s_mov_b64 s[26:27], -1
	s_and_b64 vcc, exec, s[38:39]
	global_store_dwordx4 v[234:235], v[0:3], off offset:256
	s_cbranch_vccnz .LBB0_653
	s_andn2_b64 vcc, exec, s[6:7]
	s_cbranch_vccnz .LBB0_652
	s_barrier
	s_branch .LBB0_652

;     DI bool next(int i, Unit& u) const {
;         const long L = (long)i * G + c; if (L >= nwg) return false;
;         int wgid = (int)L; { const int q = nwg / NXCD, r = nwg % NXCD, xcd = wgid % NXCD, off = wgid / NXCD; wgid = (xcd < r ? xcd * (q + 1) : r * (q + 1) + (xcd - r) * q) + off; }
;         const int nig = WGM * nN, gid = wgid / nig, fm = gid * WGM, gsz = (nM - fm) < WGM ? (nM - fm) : WGM;
;         u.pm = fm + ((wgid % nig) % gsz); const int pv_ = (wgid % nig) / gsz; u.ks = pv_ / nNr; u.pn = pv_ - u.ks * nNr; return true;
;     }
.LBB0_686:
	s_add_i32 s97, s97, 1
	s_cmp_lt_u32 s97, 2
	s_cbranch_scc1 .Lts2_slow
	s_or_b32 s4, s89, s33
	s_and_b32 s4, s4, 7
	s_cmp_lg_u32 s4, 0
	s_cbranch_scc1 .Lts2_slow
	s_cmp_lt_u32 s49, 16
	s_cbranch_scc1 .Lts2_slow
	s_lshl_b32 s4, s90, 5
	s_cmp_gt_u32 s49, s4
	s_cbranch_scc1 .Lts2_slow
	s_mul_i32 s4, s97, s33
	s_add_i32 s4, s4, s88
	s_cmp_lt_i32 s4, s54
	s_cselect_b64 s[6:7], -1, 0
	s_cbranch_scc0 .LBB0_692
	s_lshr_b32 s4, s33, 3
	s_add_i32 s99, s99, s4
	s_cmp_ge_u32 s99, s49
	s_cselect_b32 s4, s49, 0
	s_cselect_b32 s5, 1, 0
	s_sub_i32 s99, s99, s4
	s_add_i32 s98, s98, s5
	s_cmp_ge_u32 s99, s49
	s_cselect_b32 s4, s49, 0
	s_cselect_b32 s5, 1, 0
	s_sub_i32 s99, s99, s4
	s_add_i32 s98, s98, s5
	s_lshl_b32 s30, s98, 3
	s_and_b32 s4, s99, 7
	s_add_i32 s30, s30, s4
	s_lshr_b32 s73, s99, 3
	s_mov_b32 s72, 0
	s_cmp_ge_u32 s73, s90
	s_cselect_b32 s4, s90, 0
	s_cselect_b32 s5, 1, 0
	s_sub_i32 s73, s73, s4
	s_add_i32 s72, s72, s5
	s_cmp_ge_u32 s73, s90
	s_cselect_b32 s4, s90, 0
	s_cselect_b32 s5, 1, 0
	s_sub_i32 s73, s73, s4
	s_add_i32 s72, s72, s5
	s_cmp_ge_u32 s73, s90
	s_cselect_b32 s4, s90, 0
	s_cselect_b32 s5, 1, 0
	s_sub_i32 s73, s73, s4
	s_add_i32 s72, s72, s5
	s_branch .LBB0_692
.Lts2_slow:
	s_mul_i32 s4, s97, s81
	s_mul_hi_u32 s5, s97, s33
	s_add_i32 s5, s5, s4
	s_mul_i32 s4, s97, s33
	s_add_u32 s4, s4, s88
	s_addc_u32 s5, s5, s16
	v_mov_b64_e32 v[0:1], s[54:55]
	v_cmp_ge_i64_e32 vcc, s[4:5], v[0:1]
	v_cmp_lt_i64_e64 s[6:7], s[4:5], v[0:1]
	s_cbranch_vccnz .LBB0_692
	s_ashr_i32 s5, s4, 31
	s_lshr_b32 s5, s5, 29
	s_add_i32 s30, s4, s5
	s_and_b32 s5, s30, -8
	s_sub_i32 s34, s4, s5
	s_cmp_ge_i32 s34, s1
	s_mov_b64 s[4:5], -1
	s_cbranch_scc0 .LBB0_689
	s_sub_i32 s4, s34, s1
	s_mul_i32 s4, s4, s0
	s_add_i32 s35, s4, s23
	s_mov_b64 s[4:5], 0

;     DI bool next(int i, Unit& u) const {
;     ...
;         int wgid = (int)L; { const int q = nwg / NXCD, r = nwg % NXCD, xcd = wgid % NXCD, off = wgid / NXCD; wgid = (xcd < r ? xcd * (q + 1) : r * (q + 1) + (xcd - r) * q) + off; }
;         const int nig = WGM * nN, gid = wgid / nig, fm = gid * WGM, gsz = (nM - fm) < WGM ? (nM - fm) : WGM;
;         u.pm = fm + ((wgid % nig) % gsz); const int pv_ = (wgid % nig) / gsz; u.ks = pv_ / nNr; u.pn = pv_ - u.ks * nNr; return true;
.LBB0_691:
	s_ashr_i32 s4, s30, 3
	s_add_i32 s4, s35, s4
	s_abs_i32 s30, s4
	s_mul_hi_u32 s34, s30, s50
	s_mul_i32 s35, s34, s49
	s_ashr_i32 s5, s4, 31
	s_sub_i32 s30, s30, s35
	s_xor_b32 s5, s5, s48
	s_add_i32 s35, s34, 1
	s_sub_i32 s36, s30, s49
	s_cmp_ge_u32 s30, s49
	s_cselect_b32 s34, s35, s34
	s_cselect_b32 s30, s36, s30
	s_add_i32 s35, s34, 1
	s_cmp_ge_u32 s30, s49
	s_cselect_b32 s30, s35, s34
	s_xor_b32 s30, s30, s5
	s_sub_i32 s5, s30, s5
	s_lshl_b32 s30, s5, 3
	s_sub_i32 s34, s89, s30
	s_min_i32 s34, s34, 8
	s_abs_i32 s35, s34
	v_cvt_f32_u32_e32 v0, s35
	s_sub_i32 s37, 0, s35
	s_mul_i32 s5, s5, s25
	s_sub_i32 s4, s4, s5
	v_rcp_iflag_f32_e32 v0, v0
	s_abs_i32 s36, s4
	s_xor_b32 s5, s4, s34
	s_ashr_i32 s5, s5, 31
	v_mul_f32_e32 v0, 0x4f7ffffe, v0
	v_cvt_u32_f32_e32 v0, v0
	s_nop 0
	v_readfirstlane_b32 s66, v0
	s_mul_i32 s37, s37, s66
	s_mul_hi_u32 s37, s66, s37
	s_add_i32 s66, s66, s37
	s_mul_hi_u32 s37, s36, s66
	s_mul_i32 s66, s37, s35
	s_sub_i32 s36, s36, s66
	s_add_i32 s66, s37, 1
	s_sub_i32 s67, s36, s35
	s_cmp_ge_u32 s36, s35
	s_cselect_b32 s37, s66, s37
	s_cselect_b32 s36, s67, s36
	s_add_i32 s66, s37, 1
	s_cmp_ge_u32 s36, s35
	s_cselect_b32 s35, s66, s37
	s_xor_b32 s35, s35, s5
	s_sub_i32 s5, s35, s5
	s_mul_i32 s34, s5, s34
	s_sub_i32 s4, s4, s34
	s_abs_i32 s34, s5
	s_mul_hi_u32 s35, s34, s51
	s_mul_i32 s36, s35, s90
	s_sub_i32 s34, s34, s36
	s_add_i32 s30, s4, s30
	s_ashr_i32 s4, s5, 31
	s_add_i32 s36, s35, 1
	s_sub_i32 s37, s34, s90
	s_cmp_ge_u32 s34, s90
	s_cselect_b32 s35, s36, s35
	s_cselect_b32 s34, s37, s34
	s_add_i32 s36, s35, 1
	s_cmp_ge_u32 s34, s90
	s_cselect_b32 s34, s36, s35
	s_xor_b32 s34, s34, s4
	s_sub_i32 s72, s34, s4
	s_mul_i32 s4, s72, s90
	s_sub_i32 s73, s5, s4
	s_lshr_b32 s98, s30, 3
	s_mul_i32 s99, s72, s90
	s_add_i32 s99, s99, s73
	s_lshl_b32 s99, s99, 3
	s_and_b32 s4, s30, 7
	s_add_i32 s99, s99, s4

;     DI bool next(int i, Unit& u) const {
;         const long L = (long)i * G + c; if (L >= nwg) return false;
;         int wgid = (int)L; { const int q = nwg / NXCD, r = nwg % NXCD, xcd = wgid % NXCD, off = wgid / NXCD; wgid = (xcd < r ? xcd * (q + 1) : r * (q + 1) + (xcd - r) * q) + off; }
;         const int nig = WGM * nN, gid = wgid / nig, fm = gid * WGM, gsz = (nM - fm) < WGM ? (nM - fm) : WGM;
;         u.pm = fm + ((wgid % nig) % gsz); const int pv_ = (wgid % nig) / gsz; u.ks = pv_ / nNr; u.pn = pv_ - u.ks * nNr; return true;
;     }
.LBB0_749:
	s_add_i32 s68, s68, 1
	s_cmp_lt_u32 s68, 2
	s_cbranch_scc1 .Lts4_slow
	s_or_b32 s4, s89, s33
	s_and_b32 s4, s4, 7
	s_cmp_lg_u32 s4, 0
	s_cbranch_scc1 .Lts4_slow
	s_cmp_lt_u32 s67, 16
	s_cbranch_scc1 .Lts4_slow
	s_lshl_b32 s4, s90, 5
	s_cmp_gt_u32 s67, s4
	s_cbranch_scc1 .Lts4_slow
	s_mul_i32 s4, s68, s33
	s_add_i32 s4, s4, s88
	s_cmp_lt_i32 s4, s54
	s_cselect_b64 s[6:7], -1, 0
	s_cbranch_scc0 .LBB0_755
	s_lshr_b32 s4, s33, 3
	s_add_i32 s99, s99, s4
	s_cmp_ge_u32 s99, s67
	s_cselect_b32 s4, s67, 0
	s_cselect_b32 s5, 1, 0
	s_sub_i32 s99, s99, s4
	s_add_i32 s98, s98, s5
	s_cmp_ge_u32 s99, s67
	s_cselect_b32 s4, s67, 0
	s_cselect_b32 s5, 1, 0
	s_sub_i32 s99, s99, s4
	s_add_i32 s98, s98, s5
	s_lshl_b32 s72, s98, 3
	s_and_b32 s4, s99, 7
	s_add_i32 s72, s72, s4
	s_lshr_b32 s75, s99, 3
	s_mov_b32 s73, 0
	s_cmp_ge_u32 s75, s90
	s_cselect_b32 s4, s90, 0
	s_cselect_b32 s5, 1, 0
	s_sub_i32 s75, s75, s4
	s_add_i32 s73, s73, s5
	s_cmp_ge_u32 s75, s90
	s_cselect_b32 s4, s90, 0
	s_cselect_b32 s5, 1, 0
	s_sub_i32 s75, s75, s4
	s_add_i32 s73, s73, s5
	s_cmp_ge_u32 s75, s90
	s_cselect_b32 s4, s90, 0
	s_cselect_b32 s5, 1, 0
	s_sub_i32 s75, s75, s4
	s_add_i32 s73, s73, s5
	s_branch .LBB0_755
.Lts4_slow:
	s_mul_i32 s4, s68, s81
	s_mul_hi_u32 s5, s68, s33
	s_add_i32 s5, s5, s4
	s_mul_i32 s4, s68, s33
	s_add_u32 s4, s4, s88
	s_addc_u32 s5, s5, s49
	v_mov_b64_e32 v[0:1], s[54:55]
	v_cmp_ge_i64_e32 vcc, s[4:5], v[0:1]
	v_cmp_lt_i64_e64 s[6:7], s[4:5], v[0:1]
	s_cbranch_vccnz .LBB0_755
	s_ashr_i32 s5, s4, 31
	s_lshr_b32 s5, s5, 29
	s_add_i32 s30, s4, s5
	s_and_b32 s5, s30, -8
	s_sub_i32 s31, s4, s5
	s_cmp_ge_i32 s31, s51
	s_mov_b64 s[4:5], -1
	s_cbranch_scc0 .LBB0_752
	s_sub_i32 s4, s31, s51
	s_mul_i32 s4, s4, s50
	s_mul_i32 s5, s52, s51
	s_add_i32 s34, s4, s5
	s_mov_b64 s[4:5], 0

;     DI bool next(int i, Unit& u) const {
;     ...
;         int wgid = (int)L; { const int q = nwg / NXCD, r = nwg % NXCD, xcd = wgid % NXCD, off = wgid / NXCD; wgid = (xcd < r ? xcd * (q + 1) : r * (q + 1) + (xcd - r) * q) + off; }
;         const int nig = WGM * nN, gid = wgid / nig, fm = gid * WGM, gsz = (nM - fm) < WGM ? (nM - fm) : WGM;
;         u.pm = fm + ((wgid % nig) % gsz); const int pv_ = (wgid % nig) / gsz; u.ks = pv_ / nNr; u.pn = pv_ - u.ks * nNr; return true;
.LBB0_754:
	s_ashr_i32 s4, s30, 3
	s_add_i32 s4, s34, s4
	s_abs_i32 s30, s4
	s_mul_hi_u32 s31, s30, s69
	s_mul_i32 s34, s31, s67
	s_ashr_i32 s5, s4, 31
	s_sub_i32 s30, s30, s34
	s_xor_b32 s5, s5, s66
	s_add_i32 s34, s31, 1
	s_sub_i32 s35, s30, s67
	s_cmp_ge_u32 s30, s67
	s_cselect_b32 s31, s34, s31
	s_cselect_b32 s30, s35, s30
	s_add_i32 s34, s31, 1
	s_cmp_ge_u32 s30, s67
	s_cselect_b32 s30, s34, s31
	s_xor_b32 s30, s30, s5
	s_sub_i32 s5, s30, s5
	s_lshl_b32 s30, s5, 3
	s_sub_i32 s31, s89, s30
	s_min_i32 s31, s31, 8
	s_abs_i32 s34, s31
	v_cvt_f32_u32_e32 v0, s34
	s_sub_i32 s36, 0, s34
	s_mul_i32 s5, s5, s53
	s_sub_i32 s4, s4, s5
	v_rcp_iflag_f32_e32 v0, v0
	s_abs_i32 s35, s4
	s_xor_b32 s5, s4, s31
	s_ashr_i32 s5, s5, 31
	v_mul_f32_e32 v0, 0x4f7ffffe, v0
	v_cvt_u32_f32_e32 v0, v0
	s_nop 0
	v_readfirstlane_b32 s37, v0
	s_mul_i32 s36, s36, s37
	s_mul_hi_u32 s36, s37, s36
	s_add_i32 s37, s37, s36
	s_mul_hi_u32 s36, s35, s37
	s_mul_i32 s37, s36, s34
	s_sub_i32 s35, s35, s37
	s_add_i32 s37, s36, 1
	s_sub_i32 s60, s35, s34
	s_cmp_ge_u32 s35, s34
	s_cselect_b32 s36, s37, s36
	s_cselect_b32 s35, s60, s35
	s_add_i32 s37, s36, 1
	s_cmp_ge_u32 s35, s34
	s_cselect_b32 s34, s37, s36
	s_xor_b32 s34, s34, s5
	s_sub_i32 s5, s34, s5
	s_mul_i32 s31, s5, s31
	s_sub_i32 s4, s4, s31
	s_add_i32 s72, s4, s30
	s_abs_i32 s30, s5
	s_mul_hi_u32 s31, s30, s77
	s_mul_i32 s34, s31, s90
	s_sub_i32 s30, s30, s34
	s_ashr_i32 s4, s5, 31
	s_add_i32 s34, s31, 1
	s_sub_i32 s35, s30, s90
	s_cmp_ge_u32 s30, s90
	s_cselect_b32 s31, s34, s31
	s_cselect_b32 s30, s35, s30
	s_add_i32 s34, s31, 1
	s_cmp_ge_u32 s30, s90
	s_cselect_b32 s30, s34, s31
	s_xor_b32 s30, s30, s4
	s_sub_i32 s73, s30, s4
	s_mul_i32 s4, s73, s90
	s_sub_i32 s75, s5, s4
	s_lshr_b32 s98, s72, 3
	s_mul_i32 s99, s73, s90
	s_add_i32 s99, s99, s75
	s_lshl_b32 s99, s99, 3
	s_and_b32 s4, s72, 7
	s_add_i32 s99, s99, s4
